# PEER selection: softmax max taken from lane 0 (candidate (0,0) of the sorted top-16 lists is the maximum) instead of a wave-wide max reduction
# speedup vs baseline: 1.0097x; 1.0035x over previous
.LBB0_1118:
	global_load_dword v41, v[38:39], off
	global_load_dword v40, v[36:37], off
	s_waitcnt vmcnt(2)
	v_add_f32_e32 v32, v42, v43
	v_cndmask_b32_e64 v44, v197, v32, s[4:5]
	ds_write_b32 v143, v44
	ds_read_b128 v[46:49], v136
	ds_read_b128 v[50:53], v136 offset:16
	ds_read_b128 v[54:57], v136 offset:32
	ds_read_b128 v[58:61], v136 offset:48
	ds_read_b128 v[62:65], v136 offset:64
	ds_read_b128 v[66:69], v136 offset:80
	ds_read_b128 v[74:77], v136 offset:96
	ds_read_b128 v[78:81], v136 offset:112
	ds_read_b128 v[82:85], v136 offset:128
	ds_read_b128 v[86:89], v136 offset:144
	ds_read_b128 v[90:93], v136 offset:160
	ds_read_b128 v[32:35], v136 offset:176
	v_mov_b32_e32 v70, 0
	v_mov_b32_e32 v71, 0
	s_waitcnt lgkmcnt(11)
	v_cmp_gt_f32_e64 s[0:1], v46, v44
	v_cmp_gt_f32_e64 s[22:23], v47, v44
	v_cmp_gt_f32_e64 s[98:99], v48, v44
	v_cmp_gt_f32_e64 s[100:101], v49, v44
	v_addc_co_u32_e64 v70, vcc, 0, v70, s[0:1]
	v_addc_co_u32_e64 v71, vcc, 0, v71, s[22:23]
	v_addc_co_u32_e64 v70, vcc, 0, v70, s[98:99]
	v_addc_co_u32_e64 v71, vcc, 0, v71, s[100:101]
	ds_read_b128 v[46:49], v136 offset:192
	s_waitcnt lgkmcnt(11)
	v_cmp_gt_f32_e64 s[0:1], v50, v44
	v_cmp_gt_f32_e64 s[22:23], v51, v44
	v_cmp_gt_f32_e64 s[98:99], v52, v44
	v_cmp_gt_f32_e64 s[100:101], v53, v44
	v_addc_co_u32_e64 v70, vcc, 0, v70, s[0:1]
	v_addc_co_u32_e64 v71, vcc, 0, v71, s[22:23]
	v_addc_co_u32_e64 v70, vcc, 0, v70, s[98:99]
	v_addc_co_u32_e64 v71, vcc, 0, v71, s[100:101]
	s_waitcnt lgkmcnt(10)
	v_cmp_gt_f32_e64 s[0:1], v54, v44
	v_cmp_gt_f32_e64 s[22:23], v55, v44
	v_cmp_gt_f32_e64 s[98:99], v56, v44
	v_cmp_gt_f32_e64 s[100:101], v57, v44
	v_addc_co_u32_e64 v70, vcc, 0, v70, s[0:1]
	v_addc_co_u32_e64 v71, vcc, 0, v71, s[22:23]
	v_addc_co_u32_e64 v70, vcc, 0, v70, s[98:99]
	v_addc_co_u32_e64 v71, vcc, 0, v71, s[100:101]
	s_waitcnt lgkmcnt(9)
	v_cmp_gt_f32_e64 s[0:1], v58, v44
	v_cmp_gt_f32_e64 s[22:23], v59, v44
	v_cmp_gt_f32_e64 s[98:99], v60, v44
	v_cmp_gt_f32_e64 s[100:101], v61, v44
	v_addc_co_u32_e64 v70, vcc, 0, v70, s[0:1]
	v_addc_co_u32_e64 v71, vcc, 0, v71, s[22:23]
	v_addc_co_u32_e64 v70, vcc, 0, v70, s[98:99]
	v_addc_co_u32_e64 v71, vcc, 0, v71, s[100:101]
	s_waitcnt lgkmcnt(8)
	v_cmp_gt_f32_e64 s[0:1], v62, v44
	v_cmp_gt_f32_e64 s[22:23], v63, v44
	v_cmp_gt_f32_e64 s[98:99], v64, v44
	v_cmp_gt_f32_e64 s[100:101], v65, v44
	v_addc_co_u32_e64 v70, vcc, 0, v70, s[0:1]
	v_addc_co_u32_e64 v71, vcc, 0, v71, s[22:23]
	v_addc_co_u32_e64 v70, vcc, 0, v70, s[98:99]
	v_addc_co_u32_e64 v71, vcc, 0, v71, s[100:101]
	s_waitcnt lgkmcnt(7)
	v_cmp_gt_f32_e64 s[0:1], v66, v44
	v_cmp_gt_f32_e64 s[22:23], v67, v44
	v_cmp_gt_f32_e64 s[98:99], v68, v44
	v_cmp_gt_f32_e64 s[100:101], v69, v44
	v_addc_co_u32_e64 v70, vcc, 0, v70, s[0:1]
	v_addc_co_u32_e64 v71, vcc, 0, v71, s[22:23]
	v_addc_co_u32_e64 v70, vcc, 0, v70, s[98:99]
	v_addc_co_u32_e64 v71, vcc, 0, v71, s[100:101]
	s_waitcnt lgkmcnt(6)
	v_cmp_gt_f32_e64 s[0:1], v74, v44
	v_cmp_gt_f32_e64 s[22:23], v75, v44
	v_cmp_gt_f32_e64 s[98:99], v76, v44
	v_cmp_gt_f32_e64 s[100:101], v77, v44
	v_addc_co_u32_e64 v70, vcc, 0, v70, s[0:1]
	v_addc_co_u32_e64 v71, vcc, 0, v71, s[22:23]
	v_addc_co_u32_e64 v70, vcc, 0, v70, s[98:99]
	v_addc_co_u32_e64 v71, vcc, 0, v71, s[100:101]
	s_waitcnt lgkmcnt(5)
	v_cmp_gt_f32_e64 s[0:1], v78, v44
	v_cmp_gt_f32_e64 s[22:23], v79, v44
	v_cmp_gt_f32_e64 s[98:99], v80, v44
	v_cmp_gt_f32_e64 s[100:101], v81, v44
	v_addc_co_u32_e64 v70, vcc, 0, v70, s[0:1]
	v_addc_co_u32_e64 v71, vcc, 0, v71, s[22:23]
	v_addc_co_u32_e64 v70, vcc, 0, v70, s[98:99]
	v_addc_co_u32_e64 v71, vcc, 0, v71, s[100:101]
	s_waitcnt lgkmcnt(4)
	v_cmp_gt_f32_e64 s[0:1], v82, v44
	v_cmp_gt_f32_e64 s[22:23], v83, v44
	v_cmp_gt_f32_e64 s[98:99], v84, v44
	v_cmp_gt_f32_e64 s[100:101], v85, v44
	v_addc_co_u32_e64 v70, vcc, 0, v70, s[0:1]
	v_addc_co_u32_e64 v71, vcc, 0, v71, s[22:23]
	v_addc_co_u32_e64 v70, vcc, 0, v70, s[98:99]
	v_addc_co_u32_e64 v71, vcc, 0, v71, s[100:101]
	s_waitcnt lgkmcnt(3)
	v_cmp_gt_f32_e64 s[0:1], v86, v44
	v_cmp_gt_f32_e64 s[22:23], v87, v44
	v_cmp_gt_f32_e64 s[98:99], v88, v44
	v_cmp_gt_f32_e64 s[100:101], v89, v44
	v_addc_co_u32_e64 v70, vcc, 0, v70, s[0:1]
	v_addc_co_u32_e64 v71, vcc, 0, v71, s[22:23]
	v_addc_co_u32_e64 v70, vcc, 0, v70, s[98:99]
	v_addc_co_u32_e64 v71, vcc, 0, v71, s[100:101]
	s_waitcnt lgkmcnt(2)
	v_cmp_gt_f32_e64 s[0:1], v90, v44
	v_cmp_gt_f32_e64 s[22:23], v91, v44
	v_cmp_gt_f32_e64 s[98:99], v92, v44
	v_cmp_gt_f32_e64 s[100:101], v93, v44
	v_addc_co_u32_e64 v70, vcc, 0, v70, s[0:1]
	v_addc_co_u32_e64 v71, vcc, 0, v71, s[22:23]
	v_addc_co_u32_e64 v70, vcc, 0, v70, s[98:99]
	v_addc_co_u32_e64 v71, vcc, 0, v71, s[100:101]
	s_waitcnt lgkmcnt(1)
	v_cmp_gt_f32_e64 s[0:1], v32, v44
	v_cmp_gt_f32_e64 s[22:23], v33, v44
	v_cmp_gt_f32_e64 s[98:99], v34, v44
	v_cmp_gt_f32_e64 s[100:101], v35, v44
	v_addc_co_u32_e64 v70, vcc, 0, v70, s[0:1]
	v_addc_co_u32_e64 v71, vcc, 0, v71, s[22:23]
	v_addc_co_u32_e64 v70, vcc, 0, v70, s[98:99]
	v_addc_co_u32_e64 v71, vcc, 0, v71, s[100:101]
	s_waitcnt lgkmcnt(0)
	v_cmp_gt_f32_e64 s[0:1], v46, v44
	v_cmp_gt_f32_e64 s[22:23], v47, v44
	v_cmp_gt_f32_e64 s[98:99], v48, v44
	v_cmp_gt_f32_e64 s[100:101], v49, v44
	v_addc_co_u32_e64 v70, vcc, 0, v70, s[0:1]
	v_addc_co_u32_e64 v71, vcc, 0, v71, s[22:23]
	v_addc_co_u32_e64 v70, vcc, 0, v70, s[98:99]
	v_addc_co_u32_e64 v71, vcc, 0, v71, s[100:101]
	v_readlane_b32 s0, v44, 0
	v_add_u32_e32 v33, v70, v71
	s_nop 1
	v_subrev_f32_e32 v32, s0, v44
	v_mul_f32_e32 v32, 0x3fb8aa3b, v32
	v_exp_f32_e32 v32, v32
	v_cmp_gt_i32_e32 vcc, 16, v33
	s_and_b64 vcc, s[4:5], vcc
	s_nop 0
	v_cndmask_b32_e32 v34, 0, v32, vcc
	s_mov_b64 s[100:101], vcc
	s_nop 0
	v_add_f32_dpp v35, v34, v34 quad_perm:[1,0,3,2] row_mask:0xf bank_mask:0xf
	s_nop 1
	v_add_f32_dpp v34, v35, v35 quad_perm:[2,3,0,1] row_mask:0xf bank_mask:0xf
	s_nop 1
	v_add_f32_dpp v35, v34, v34 row_half_mirror row_mask:0xf bank_mask:0xf
	s_nop 1
	v_add_f32_dpp v34, v35, v35 row_mirror row_mask:0xf bank_mask:0xf
	s_nop 1
	v_readlane_b32 s22, v34, 0
	v_readlane_b32 s23, v34, 16
	v_readlane_b32 s98, v34, 32
	v_readlane_b32 s99, v34, 48
	s_nop 1
	v_mov_b32_e32 v34, s22
	v_add_f32_e32 v34, s23, v34
	v_add_f32_e32 v34, s98, v34
	v_add_f32_e32 v34, s99, v34
	s_mov_b64 vcc, s[100:101]
	s_mov_b64 s[22:23], 0
	s_and_saveexec_b64 s[0:1], vcc
	s_cbranch_execz .Lpf_a_skip
	v_lshlrev_b32_e32 v35, 7, v42
	v_and_b32_e32 v51, 0x7f, v43
	v_div_scale_f32 v52, s[22:23], v34, v34, v32
	v_rcp_f32_e32 v53, v52
	v_and_or_b32 v35, v35, s31, v51
	v_add_u32_e32 v33, s24, v33
	v_lshl_add_u32 v33, v33, 2, v136
	v_fma_f32 v51, -v52, v53, 1.0
	v_fmac_f32_e32 v53, v51, v53
	v_div_scale_f32 v51, vcc, v32, v34, v32
	v_mul_f32_e32 v54, v51, v53
	v_fma_f32 v55, -v52, v54, v51
	v_fmac_f32_e32 v54, v55, v53
	v_fma_f32 v51, -v52, v54, v51
	v_div_fmas_f32 v51, v51, v53, v54
	v_div_fixup_f32 v32, v51, v34, v32
	ds_write2st64_b32 v33, v35, v32 offset0:1 offset1:3
	ds_read_b32 v34, v33 offset:256
	s_waitcnt lgkmcnt(0)
	v_cmp_ne_u32_e64 s[22:23], v34, v35

.LBB0_1322:
	s_waitcnt vmcnt(0)
	v_add_f32_e32 v32, v41, v40
	v_cndmask_b32_e64 v36, v197, v32, s[4:5]
	ds_write_b32 v143, v36
	ds_read_b128 v[46:49], v136
	ds_read_b128 v[50:53], v136 offset:16
	ds_read_b128 v[54:57], v136 offset:32
	ds_read_b128 v[58:61], v136 offset:48
	ds_read_b128 v[62:65], v136 offset:64
	ds_read_b128 v[66:69], v136 offset:80
	ds_read_b128 v[74:77], v136 offset:96
	ds_read_b128 v[78:81], v136 offset:112
	ds_read_b128 v[82:85], v136 offset:128
	ds_read_b128 v[86:89], v136 offset:144
	ds_read_b128 v[90:93], v136 offset:160
	ds_read_b128 v[32:35], v136 offset:176
	v_mov_b32_e32 v70, 0
	v_mov_b32_e32 v71, 0
	s_waitcnt lgkmcnt(11)
	v_cmp_gt_f32_e64 s[0:1], v46, v36
	v_cmp_gt_f32_e64 s[22:23], v47, v36
	v_cmp_gt_f32_e64 s[98:99], v48, v36
	v_cmp_gt_f32_e64 s[100:101], v49, v36
	v_addc_co_u32_e64 v70, vcc, 0, v70, s[0:1]
	v_addc_co_u32_e64 v71, vcc, 0, v71, s[22:23]
	v_addc_co_u32_e64 v70, vcc, 0, v70, s[98:99]
	v_addc_co_u32_e64 v71, vcc, 0, v71, s[100:101]
	ds_read_b128 v[46:49], v136 offset:192
	s_waitcnt lgkmcnt(11)
	v_cmp_gt_f32_e64 s[0:1], v50, v36
	v_cmp_gt_f32_e64 s[22:23], v51, v36
	v_cmp_gt_f32_e64 s[98:99], v52, v36
	v_cmp_gt_f32_e64 s[100:101], v53, v36
	v_addc_co_u32_e64 v70, vcc, 0, v70, s[0:1]
	v_addc_co_u32_e64 v71, vcc, 0, v71, s[22:23]
	v_addc_co_u32_e64 v70, vcc, 0, v70, s[98:99]
	v_addc_co_u32_e64 v71, vcc, 0, v71, s[100:101]
	s_waitcnt lgkmcnt(10)
	v_cmp_gt_f32_e64 s[0:1], v54, v36
	v_cmp_gt_f32_e64 s[22:23], v55, v36
	v_cmp_gt_f32_e64 s[98:99], v56, v36
	v_cmp_gt_f32_e64 s[100:101], v57, v36
	v_addc_co_u32_e64 v70, vcc, 0, v70, s[0:1]
	v_addc_co_u32_e64 v71, vcc, 0, v71, s[22:23]
	v_addc_co_u32_e64 v70, vcc, 0, v70, s[98:99]
	v_addc_co_u32_e64 v71, vcc, 0, v71, s[100:101]
	s_waitcnt lgkmcnt(9)
	v_cmp_gt_f32_e64 s[0:1], v58, v36
	v_cmp_gt_f32_e64 s[22:23], v59, v36
	v_cmp_gt_f32_e64 s[98:99], v60, v36
	v_cmp_gt_f32_e64 s[100:101], v61, v36
	v_addc_co_u32_e64 v70, vcc, 0, v70, s[0:1]
	v_addc_co_u32_e64 v71, vcc, 0, v71, s[22:23]
	v_addc_co_u32_e64 v70, vcc, 0, v70, s[98:99]
	v_addc_co_u32_e64 v71, vcc, 0, v71, s[100:101]
	s_waitcnt lgkmcnt(8)
	v_cmp_gt_f32_e64 s[0:1], v62, v36
	v_cmp_gt_f32_e64 s[22:23], v63, v36
	v_cmp_gt_f32_e64 s[98:99], v64, v36
	v_cmp_gt_f32_e64 s[100:101], v65, v36
	v_addc_co_u32_e64 v70, vcc, 0, v70, s[0:1]
	v_addc_co_u32_e64 v71, vcc, 0, v71, s[22:23]
	v_addc_co_u32_e64 v70, vcc, 0, v70, s[98:99]
	v_addc_co_u32_e64 v71, vcc, 0, v71, s[100:101]
	s_waitcnt lgkmcnt(7)
	v_cmp_gt_f32_e64 s[0:1], v66, v36
	v_cmp_gt_f32_e64 s[22:23], v67, v36
	v_cmp_gt_f32_e64 s[98:99], v68, v36
	v_cmp_gt_f32_e64 s[100:101], v69, v36
	v_addc_co_u32_e64 v70, vcc, 0, v70, s[0:1]
	v_addc_co_u32_e64 v71, vcc, 0, v71, s[22:23]
	v_addc_co_u32_e64 v70, vcc, 0, v70, s[98:99]
	v_addc_co_u32_e64 v71, vcc, 0, v71, s[100:101]
	s_waitcnt lgkmcnt(6)
	v_cmp_gt_f32_e64 s[0:1], v74, v36
	v_cmp_gt_f32_e64 s[22:23], v75, v36
	v_cmp_gt_f32_e64 s[98:99], v76, v36
	v_cmp_gt_f32_e64 s[100:101], v77, v36
	v_addc_co_u32_e64 v70, vcc, 0, v70, s[0:1]
	v_addc_co_u32_e64 v71, vcc, 0, v71, s[22:23]
	v_addc_co_u32_e64 v70, vcc, 0, v70, s[98:99]
	v_addc_co_u32_e64 v71, vcc, 0, v71, s[100:101]
	s_waitcnt lgkmcnt(5)
	v_cmp_gt_f32_e64 s[0:1], v78, v36
	v_cmp_gt_f32_e64 s[22:23], v79, v36
	v_cmp_gt_f32_e64 s[98:99], v80, v36
	v_cmp_gt_f32_e64 s[100:101], v81, v36
	v_addc_co_u32_e64 v70, vcc, 0, v70, s[0:1]
	v_addc_co_u32_e64 v71, vcc, 0, v71, s[22:23]
	v_addc_co_u32_e64 v70, vcc, 0, v70, s[98:99]
	v_addc_co_u32_e64 v71, vcc, 0, v71, s[100:101]
	s_waitcnt lgkmcnt(4)
	v_cmp_gt_f32_e64 s[0:1], v82, v36
	v_cmp_gt_f32_e64 s[22:23], v83, v36
	v_cmp_gt_f32_e64 s[98:99], v84, v36
	v_cmp_gt_f32_e64 s[100:101], v85, v36
	v_addc_co_u32_e64 v70, vcc, 0, v70, s[0:1]
	v_addc_co_u32_e64 v71, vcc, 0, v71, s[22:23]
	v_addc_co_u32_e64 v70, vcc, 0, v70, s[98:99]
	v_addc_co_u32_e64 v71, vcc, 0, v71, s[100:101]
	s_waitcnt lgkmcnt(3)
	v_cmp_gt_f32_e64 s[0:1], v86, v36
	v_cmp_gt_f32_e64 s[22:23], v87, v36
	v_cmp_gt_f32_e64 s[98:99], v88, v36
	v_cmp_gt_f32_e64 s[100:101], v89, v36
	v_addc_co_u32_e64 v70, vcc, 0, v70, s[0:1]
	v_addc_co_u32_e64 v71, vcc, 0, v71, s[22:23]
	v_addc_co_u32_e64 v70, vcc, 0, v70, s[98:99]
	v_addc_co_u32_e64 v71, vcc, 0, v71, s[100:101]
	s_waitcnt lgkmcnt(2)
	v_cmp_gt_f32_e64 s[0:1], v90, v36
	v_cmp_gt_f32_e64 s[22:23], v91, v36
	v_cmp_gt_f32_e64 s[98:99], v92, v36
	v_cmp_gt_f32_e64 s[100:101], v93, v36
	v_addc_co_u32_e64 v70, vcc, 0, v70, s[0:1]
	v_addc_co_u32_e64 v71, vcc, 0, v71, s[22:23]
	v_addc_co_u32_e64 v70, vcc, 0, v70, s[98:99]
	v_addc_co_u32_e64 v71, vcc, 0, v71, s[100:101]
	s_waitcnt lgkmcnt(1)
	v_cmp_gt_f32_e64 s[0:1], v32, v36
	v_cmp_gt_f32_e64 s[22:23], v33, v36
	v_cmp_gt_f32_e64 s[98:99], v34, v36
	v_cmp_gt_f32_e64 s[100:101], v35, v36
	v_addc_co_u32_e64 v70, vcc, 0, v70, s[0:1]
	v_addc_co_u32_e64 v71, vcc, 0, v71, s[22:23]
	v_addc_co_u32_e64 v70, vcc, 0, v70, s[98:99]
	v_addc_co_u32_e64 v71, vcc, 0, v71, s[100:101]
	s_waitcnt lgkmcnt(0)
	v_cmp_gt_f32_e64 s[0:1], v46, v36
	v_cmp_gt_f32_e64 s[22:23], v47, v36
	v_cmp_gt_f32_e64 s[98:99], v48, v36
	v_cmp_gt_f32_e64 s[100:101], v49, v36
	v_addc_co_u32_e64 v70, vcc, 0, v70, s[0:1]
	v_addc_co_u32_e64 v71, vcc, 0, v71, s[22:23]
	v_addc_co_u32_e64 v70, vcc, 0, v70, s[98:99]
	v_addc_co_u32_e64 v71, vcc, 0, v71, s[100:101]
	v_readlane_b32 s0, v36, 0
	v_add_u32_e32 v33, v70, v71
	s_nop 1
	v_subrev_f32_e32 v32, s0, v36
	v_mul_f32_e32 v32, 0x3fb8aa3b, v32
	v_exp_f32_e32 v32, v32
	v_cmp_gt_i32_e32 vcc, 16, v33
	s_and_b64 vcc, s[4:5], vcc
	s_nop 0
	v_cndmask_b32_e32 v34, 0, v32, vcc
	s_mov_b64 s[100:101], vcc
	s_nop 0
	v_add_f32_dpp v35, v34, v34 quad_perm:[1,0,3,2] row_mask:0xf bank_mask:0xf
	s_nop 1
	v_add_f32_dpp v34, v35, v35 quad_perm:[2,3,0,1] row_mask:0xf bank_mask:0xf
	s_nop 1
	v_add_f32_dpp v35, v34, v34 row_half_mirror row_mask:0xf bank_mask:0xf
	s_nop 1
	v_add_f32_dpp v34, v35, v35 row_mirror row_mask:0xf bank_mask:0xf
	s_nop 1
	v_readlane_b32 s22, v34, 0
	v_readlane_b32 s23, v34, 16
	v_readlane_b32 s98, v34, 32
	v_readlane_b32 s99, v34, 48
	s_nop 1
	v_mov_b32_e32 v34, s22
	v_add_f32_e32 v34, s23, v34
	v_add_f32_e32 v34, s98, v34
	v_add_f32_e32 v34, s99, v34
	s_mov_b64 vcc, s[100:101]
	s_mov_b64 s[22:23], 0
	s_and_saveexec_b64 s[0:1], vcc
	s_cbranch_execz .Lpf_b_skip
	v_lshlrev_b32_e32 v35, 7, v41
	v_and_b32_e32 v51, 0x7f, v40
	v_div_scale_f32 v52, s[22:23], v34, v34, v32
	v_rcp_f32_e32 v53, v52
	v_and_or_b32 v35, v35, s31, v51
	v_lshl_add_u32 v33, v33, 2, v136
	v_fma_f32 v51, -v52, v53, 1.0
	v_fmac_f32_e32 v53, v51, v53
	v_div_scale_f32 v51, vcc, v32, v34, v32
	v_mul_f32_e32 v54, v51, v53
	v_fma_f32 v55, -v52, v54, v51
	v_fmac_f32_e32 v54, v55, v53
	v_fma_f32 v51, -v52, v54, v51
	v_div_fmas_f32 v51, v51, v53, v54
	v_div_fixup_f32 v32, v51, v34, v32
	v_add_u32_e32 v33, 0xc0, v33
	ds_write2st64_b32 v33, v35, v32 offset0:2 offset1:4
	ds_read_b32 v34, v33 offset:512
	s_waitcnt lgkmcnt(0)
	v_cmp_ne_u32_e64 s[22:23], v34, v35
